# v23 + same lazy-rescale branch-test trim in the band-prompt attention loop (both unrolled halves)
# speedup vs baseline: 1.0077x; 1.0021x over previous
; __device__ __forceinline__ float halves_max(float m) { auto rr = __builtin_amdgcn_permlane32_swap(__float_as_uint(m), __float_as_uint(m), false, false); return fmaxf(__uint_as_float(rr[0]), __uint_as_float(rr[1])); }
; #define MX3_(a, b, c) __builtin_fmaxf(__builtin_fmaxf((a), (b)), (c))
; template <int MODE> __device__ __forceinline__ void st_sm(int T, int tq, int qpos, int hi, const LAS float* biasl, f32x16& s0, f32x16& s1, f32x16& o0, f32x16& o1, f32x16& negm, float& lrun, bool& fresh) {
;     ...
;     float ma = MX3_(s0[0], s0[1], s1[0]), mb = MX3_(s0[2], s0[3], s1[1]); ma = MX3_(ma, s1[2], s1[3]);
; #pragma unroll
;     for (int i = 4; i < 16; i += 4) { ma = MX3_(ma, s0[i], s0[i + 1]); mb = MX3_(mb, s0[i + 2], s0[i + 3]); ma = MX3_(ma, s1[i], s1[i + 1]); mb = MX3_(mb, s1[i + 2], s1[i + 3]); }
;     ...
;     float mx = halves_max(__builtin_fmaxf(ma, mb));
;     if (fresh || __any(mx > 6.0f)) {
;         const float dl = fresh ? mx : fmaxf(mx, 0.f), al = __builtin_amdgcn_exp2f(-dl); lrun *= al; fresh = false;
;         const float dn = (MODE == 0) ? dl : dl * (8.0f / LOG2E);
; #pragma unroll
;         for (int i = 0; i < 16; ++i) { s0[i] -= dl; s1[i] -= dl; o0[i] *= al; o1[i] *= al; negm[i] -= dn; } }
.LBB0_604:
	v_max_f32_e32 v2, v67, v67
	v_max_f32_e32 v82, v66, v66
	v_max_f32_e32 v2, v82, v2
	v_max3_f32 v82, v68, v69, v17
	v_max3_f32 v2, v2, v16, v174
	v_max3_f32 v2, v2, v175, v70
	v_max3_f32 v82, v82, v72, v73
	v_max3_f32 v2, v2, v71, v176
	v_max3_f32 v82, v82, v180, v181
	v_max3_f32 v2, v2, v177, v74
	v_max3_f32 v82, v82, v76, v77
	v_max3_f32 v2, v2, v75, v178
	v_max3_f32 v82, v82, v182, v183
	v_max3_f32 v2, v2, v179, v78
	v_max3_f32 v82, v82, v80, v81
	v_max3_f32 v2, v2, v79, v184
	v_max3_f32 v82, v82, v186, v188
	v_max3_f32 v2, v2, v185, v82
	v_mov_b32_e32 v82, v2
	s_nop 1
	v_permlane32_swap_b32_e32 v2, v82
	s_xor_b64 s[0:1], s[4:5], -1
	v_max_f32_e32 v2, v2, v82
	s_and_b64 vcc, exec, s[0:1]
	s_cbranch_vccz .Lrs2
	v_cmp_lt_f32_e32 vcc, s58, v2
	s_cmp_lg_u64 vcc, 0
	s_cbranch_scc0 .LBB0_610
.Lrs2:
	v_max_f32_e32 v82, v2, v2
	v_max_f32_e32 v82, 0, v82
	v_cndmask_b32_e64 v2, v82, v2, s[4:5]
	v_exp_f32_e64 v82, -v2
	v_mov_b32_e32 v187, v188
	v_pk_add_f32 v[186:187], v[186:187], v[2:3] op_sel_hi:[1,0] neg_lo:[0,1] neg_hi:[0,1]
	v_pk_add_f32 v[66:67], v[66:67], v[2:3] op_sel_hi:[1,0] neg_lo:[0,1] neg_hi:[0,1]
	v_sub_f32_e32 v16, v16, v2
	v_sub_f32_e32 v17, v17, v2
	v_mul_f32_e32 v192, v192, v82
	v_pk_add_f32 v[68:69], v[68:69], v[2:3] op_sel_hi:[1,0] neg_lo:[0,1] neg_hi:[0,1]
	v_pk_add_f32 v[174:175], v[174:175], v[2:3] op_sel_hi:[1,0] neg_lo:[0,1] neg_hi:[0,1]
	v_pk_add_f32 v[70:71], v[70:71], v[2:3] op_sel_hi:[1,0] neg_lo:[0,1] neg_hi:[0,1]
	v_pk_add_f32 v[176:177], v[176:177], v[2:3] op_sel_hi:[1,0] neg_lo:[0,1] neg_hi:[0,1]
	v_pk_add_f32 v[72:73], v[72:73], v[2:3] op_sel_hi:[1,0] neg_lo:[0,1] neg_hi:[0,1]
	v_pk_add_f32 v[180:181], v[180:181], v[2:3] op_sel_hi:[1,0] neg_lo:[0,1] neg_hi:[0,1]
	v_pk_add_f32 v[74:75], v[74:75], v[2:3] op_sel_hi:[1,0] neg_lo:[0,1] neg_hi:[0,1]
	v_pk_add_f32 v[178:179], v[178:179], v[2:3] op_sel_hi:[1,0] neg_lo:[0,1] neg_hi:[0,1]
	v_pk_add_f32 v[76:77], v[76:77], v[2:3] op_sel_hi:[1,0] neg_lo:[0,1] neg_hi:[0,1]
	v_pk_add_f32 v[182:183], v[182:183], v[2:3] op_sel_hi:[1,0] neg_lo:[0,1] neg_hi:[0,1]
	v_pk_add_f32 v[78:79], v[78:79], v[2:3] op_sel_hi:[1,0] neg_lo:[0,1] neg_hi:[0,1]
	v_pk_add_f32 v[184:185], v[184:185], v[2:3] op_sel_hi:[1,0] neg_lo:[0,1] neg_hi:[0,1]
	v_pk_add_f32 v[80:81], v[80:81], v[2:3] op_sel_hi:[1,0] neg_lo:[0,1] neg_hi:[0,1]
	v_pk_mul_f32 v[48:49], v[48:49], v[82:83] op_sel_hi:[1,0]
	v_pk_mul_f32 v[46:47], v[46:47], v[82:83] op_sel_hi:[1,0]
	v_pk_mul_f32 v[44:45], v[44:45], v[82:83] op_sel_hi:[1,0]
	v_pk_mul_f32 v[42:43], v[42:43], v[82:83] op_sel_hi:[1,0]
	v_pk_mul_f32 v[40:41], v[40:41], v[82:83] op_sel_hi:[1,0]
	v_pk_mul_f32 v[38:39], v[38:39], v[82:83] op_sel_hi:[1,0]
	v_pk_mul_f32 v[36:37], v[36:37], v[82:83] op_sel_hi:[1,0]
	v_pk_mul_f32 v[34:35], v[34:35], v[82:83] op_sel_hi:[1,0]
	v_pk_mul_f32 v[32:33], v[32:33], v[82:83] op_sel_hi:[1,0]
	v_pk_mul_f32 v[30:31], v[30:31], v[82:83] op_sel_hi:[1,0]
	v_pk_mul_f32 v[28:29], v[28:29], v[82:83] op_sel_hi:[1,0]
	v_pk_mul_f32 v[26:27], v[26:27], v[82:83] op_sel_hi:[1,0]
	v_pk_mul_f32 v[24:25], v[24:25], v[82:83] op_sel_hi:[1,0]
	v_pk_mul_f32 v[22:23], v[22:23], v[82:83] op_sel_hi:[1,0]
	v_pk_mul_f32 v[20:21], v[20:21], v[82:83] op_sel_hi:[1,0]
	v_pk_mul_f32 v[18:19], v[18:19], v[82:83] op_sel_hi:[1,0]
	v_fmamk_f32 v65, v2, 0xc0b17218, v65
	v_fmamk_f32 v64, v2, 0xc0b17218, v64
	v_fmamk_f32 v63, v2, 0xc0b17218, v63
	v_fmamk_f32 v62, v2, 0xc0b17218, v62
	v_fmamk_f32 v61, v2, 0xc0b17218, v61
	v_fmamk_f32 v60, v2, 0xc0b17218, v60
	v_fmamk_f32 v59, v2, 0xc0b17218, v59
	v_fmamk_f32 v58, v2, 0xc0b17218, v58
	v_fmamk_f32 v57, v2, 0xc0b17218, v57
	v_fmamk_f32 v56, v2, 0xc0b17218, v56
	v_fmamk_f32 v55, v2, 0xc0b17218, v55
	v_fmamk_f32 v54, v2, 0xc0b17218, v54
	v_fmamk_f32 v53, v2, 0xc0b17218, v53
	v_fmamk_f32 v52, v2, 0xc0b17218, v52
	v_fmamk_f32 v51, v2, 0xc0b17218, v51
	v_fmac_f32_e32 v50, 0xc0b17218, v2
	v_mov_b32_e32 v188, v187

; __device__ __forceinline__ float halves_max(float m) { auto rr = __builtin_amdgcn_permlane32_swap(__float_as_uint(m), __float_as_uint(m), false, false); return fmaxf(__uint_as_float(rr[0]), __uint_as_float(rr[1])); }
; #define MX3_(a, b, c) __builtin_fmaxf(__builtin_fmaxf((a), (b)), (c))
; template <int MODE> __device__ __forceinline__ void st_sm(int T, int tq, int qpos, int hi, const LAS float* biasl, f32x16& s0, f32x16& s1, f32x16& o0, f32x16& o1, f32x16& negm, float& lrun, bool& fresh) {
;     ...
;     float ma = MX3_(s0[0], s0[1], s1[0]), mb = MX3_(s0[2], s0[3], s1[1]); ma = MX3_(ma, s1[2], s1[3]);
; #pragma unroll
;     for (int i = 4; i < 16; i += 4) { ma = MX3_(ma, s0[i], s0[i + 1]); mb = MX3_(mb, s0[i + 2], s0[i + 3]); ma = MX3_(ma, s1[i], s1[i + 1]); mb = MX3_(mb, s1[i + 2], s1[i + 3]); }
;     ...
;     float mx = halves_max(__builtin_fmaxf(ma, mb));
;     if (fresh || __any(mx > 6.0f)) {
.LBB0_622:
	v_max_f32_e32 v2, v67, v67
	v_max_f32_e32 v82, v66, v66
	v_max_f32_e32 v2, v82, v2
	v_max3_f32 v82, v68, v69, v17
	v_max3_f32 v2, v2, v16, v174
	v_max3_f32 v2, v2, v175, v70
	v_max3_f32 v82, v82, v72, v73
	v_max3_f32 v2, v2, v71, v176
	v_max3_f32 v82, v82, v180, v181
	v_max3_f32 v2, v2, v177, v74
	v_max3_f32 v82, v82, v76, v77
	v_max3_f32 v2, v2, v75, v178
	v_max3_f32 v82, v82, v182, v183
	v_max3_f32 v2, v2, v179, v78
	v_max3_f32 v82, v82, v80, v81
	v_max3_f32 v2, v2, v79, v184
	v_max3_f32 v82, v82, v186, v188
	v_max3_f32 v2, v2, v185, v82
	v_mov_b32_e32 v82, v2
	s_nop 1
	v_permlane32_swap_b32_e32 v2, v82
	s_xor_b64 s[0:1], s[4:5], -1
	v_max_f32_e32 v2, v2, v82
	s_and_b64 vcc, exec, s[0:1]
	s_cbranch_vccz .Lrs3
	v_cmp_lt_f32_e32 vcc, s58, v2
	s_cmp_lg_u64 vcc, 0
	s_cbranch_scc0 .LBB0_629
	s_branch .Lrs3
